# glutail phase: all ten loads of an item issued up front (one round trip instead of five), same add order
# baseline (speedup 1.0000x reference)
.LBB0_725:
	v_alignbit_b32 v0, v5, v4, 8
	v_lshrrev_b64 v[18:19], 8, v[4:5]
	v_or_b32_e32 v22, 0x4000, v0
	v_and_b32_e32 v0, 0x7c, v15
	s_movk_i32 s4, 0x700
	v_and_or_b32 v20, v14, s4, v0
	v_lshlrev_b64 v[18:19], 13, v[18:19]
	v_and_b32_e32 v17, 0x3fc, v15
	v_lshl_add_u64 v[18:19], s[8:9], 0, v[18:19]
	v_lshlrev_b32_e32 v20, 2, v20
	v_mov_b32_e32 v21, v1
	v_lshlrev_b32_e32 v0, 2, v17
	v_lshl_add_u64 v[24:25], v[18:19], 0, v[20:21]
	global_load_dwordx4 v[6:9], v0, s[16:17]
	global_load_dwordx4 v[10:13], v0, s[10:11]
	global_load_dwordx4 v[18:21], v[24:25], off
	global_load_dwordx4 v[30:33], v[24:25], off offset:512
	s_mov_b32 s4, 0x200000
	v_mov_b32_e32 v23, v1
	v_lshl_add_u64 v[4:5], v[4:5], 0, s[54:55]
	v_add_u32_e32 v14, s2, v14
	v_add_u32_e32 v15, s3, v15
	v_add_co_u32_e32 v42, vcc, s4, v24
	s_nop 1
	v_addc_co_u32_e32 v43, vcc, 0, v25, vcc
	global_load_dwordx4 v[34:37], v[42:43], off
	global_load_dwordx4 v[38:41], v[42:43], off offset:512
	s_movk_i32 s4, 0x4080
	v_cmp_gt_u32_e32 vcc, s4, v22
	s_movk_i32 s4, 0x1c00
	v_mad_u64_u32 v[24:25], s[4:5], v22, s4, v[2:3]
	s_mov_b32 s4, 0x3281000
	v_lshlrev_b64 v[22:23], 11, v[22:23]
	v_cndmask_b32_e32 v44, 0, v16, vcc
	v_mov_b32_e32 v45, v1
	v_lshl_add_u64 v[44:45], s[48:49], 0, v[44:45]
	v_lshl_add_u64 v[44:45], v[44:45], 0, v[0:1]
	v_lshlrev_b32_e32 v0, 1, v17
	v_lshl_add_u64 v[24:25], v[24:25], 0, v[0:1]
	v_add_co_u32_e32 v24, vcc, s4, v24
	v_lshl_add_u64 v[26:27], s[62:63], 0, v[22:23]
	v_lshl_add_u64 v[22:23], s[90:91], 0, v[22:23]
	v_addc_co_u32_e32 v25, vcc, 0, v25, vcc
	v_lshl_add_u64 v[26:27], v[26:27], 0, v[0:1]
	v_lshl_add_u64 v[22:23], v[22:23], 0, v[0:1]
	global_load_dwordx2 v[24:25], v[24:25], off offset:1024
	global_load_dwordx2 v[28:29], v[26:27], off
	global_load_dwordx2 v[22:23], v[22:23], off
	global_load_dwordx4 v[46:49], v[44:45], off
	s_waitcnt vmcnt(0)
	v_pk_add_f32 v[20:21], v[8:9], v[20:21]
	v_pk_add_f32 v[18:19], v[6:7], v[18:19]
	v_pk_add_f32 v[12:13], v[12:13], v[32:33]
	v_pk_add_f32 v[50:51], v[10:11], v[30:31]
	v_pk_add_f32 v[6:7], v[20:21], v[36:37]
	v_pk_add_f32 v[10:11], v[18:19], v[34:35]
	v_pk_add_f32 v[8:9], v[12:13], v[40:41]
	v_pk_add_f32 v[12:13], v[50:51], v[38:39]
	v_mul_f32_e32 v12, 0xbfb8aa3b, v12
	v_exp_f32_e32 v12, v12
	v_mul_f32_e32 v8, 0xbfb8aa3b, v8
	v_add_f32_e32 v12, 1.0, v12
	v_rcp_f32_e32 v12, v12
	v_exp_f32_e32 v8, v8
	s_mov_b64 s[4:5], 0xffff
	v_cmp_lt_u64_e32 vcc, s[4:5], v[4:5]
	s_or_b64 s[12:13], vcc, s[12:13]
	v_add_f32_e32 v8, 1.0, v8
	v_rcp_f32_e32 v8, v8
	v_lshlrev_b32_e32 v0, 16, v28
	v_lshlrev_b32_e32 v17, 16, v22
	v_fmac_f32_e32 v0, v46, v17
	v_lshlrev_b32_e32 v17, 16, v24
	v_mul_f32_e32 v17, 0xbfb8aa3b, v17
	v_exp_f32_e32 v17, v17
	s_nop 0
	v_add_f32_e32 v17, 1.0, v17
	v_rcp_f32_e32 v17, v17
	s_nop 0
	v_mul_f32_e32 v10, v10, v17
	v_fmac_f32_e32 v0, v12, v10
	v_and_b32_e32 v10, 0xffff0000, v28
	v_and_b32_e32 v12, 0xffff0000, v22
	v_fmac_f32_e32 v10, v47, v12
	v_and_b32_e32 v12, 0xffff0000, v24
	v_mul_f32_e32 v12, 0xbfb8aa3b, v12
	v_exp_f32_e32 v12, v12
	s_nop 0
	v_add_f32_e32 v12, 1.0, v12
	v_rcp_f32_e32 v12, v12
	s_nop 0
	v_mul_f32_e32 v11, v11, v12
	v_mul_f32_e32 v12, 0xbfb8aa3b, v13
	v_exp_f32_e32 v12, v12
	s_nop 0
	v_add_f32_e32 v12, 1.0, v12
	v_rcp_f32_e32 v12, v12
	s_nop 0
	v_fmac_f32_e32 v10, v12, v11
	v_lshlrev_b32_e32 v11, 16, v29
	v_lshlrev_b32_e32 v12, 16, v23
	v_fmac_f32_e32 v11, v48, v12
	v_lshlrev_b32_e32 v12, 16, v25
	v_mul_f32_e32 v12, 0xbfb8aa3b, v12
	v_exp_f32_e32 v12, v12
	s_nop 0
	v_add_f32_e32 v12, 1.0, v12
	v_rcp_f32_e32 v12, v12
	s_nop 0
	v_mul_f32_e32 v6, v6, v12
	v_fmac_f32_e32 v11, v8, v6
	v_and_b32_e32 v8, 0xffff0000, v29
	v_and_b32_e32 v6, 0xffff0000, v23
	v_fmac_f32_e32 v8, v49, v6
	v_and_b32_e32 v6, 0xffff0000, v25
	v_mul_f32_e32 v6, 0xbfb8aa3b, v6
	v_exp_f32_e32 v6, v6
	s_nop 0
	v_add_f32_e32 v6, 1.0, v6
	v_rcp_f32_e32 v6, v6
	s_nop 0
	v_mul_f32_e32 v6, v7, v6
	v_mul_f32_e32 v7, 0xbfb8aa3b, v9
	v_exp_f32_e32 v7, v7
	s_nop 0
	v_add_f32_e32 v7, 1.0, v7
	v_rcp_f32_e32 v7, v7
	s_nop 0
	v_fmac_f32_e32 v8, v7, v6
	v_cvt_pk_bf16_f32 v6, v0, v10
	v_cvt_pk_bf16_f32 v7, v11, v8
	global_store_dwordx2 v[26:27], v[6:7], off
	s_andn2_b64 exec, exec, s[12:13]
	s_cbranch_execnz .LBB0_725
